# attention MODE0 steady: first QK MFMA placed at the head of each step right after the barrier
# baseline (speedup 1.0000x reference)
.LBB0_798:
	v_mfma_f32_32x32x16_bf16 v[100:115], v[180:183], v[116:119], v[36:51]
	v_bfe_i32 v196, v132, s101, 1
	v_add_u32_e32 v197, s10, v219
	ds_read_b64_tr_b16 v[184:185], v197 offset:24576
	ds_read_b64_tr_b16 v[186:187], v197 offset:25088
	v_add_f32_e32 v84, v68, v69
	v_add_f32_e32 v84, v70, v84
	v_add_f32_e32 v84, v71, v84
	v_cvt_pk_bf16_f32 v68, v68, v69
	v_add_f32_e32 v84, v72, v84
	v_and_b32_e32 v148, v68, v196
	v_cvt_pk_bf16_f32 v68, v70, v71
	v_add_f32_e32 v84, v73, v84
	v_and_b32_e32 v149, v68, v196
	ds_read_b64_tr_b16 v[180:181], v197 offset:28672
	ds_read_b64_tr_b16 v[182:183], v197 offset:29184
	v_add_f32_e32 v68, v74, v84
	v_mfma_f32_32x32x16_bf16 v[84:99], v[176:179], v[116:119], v[36:51]
	v_add_f32_e32 v68, v75, v68
	v_add_f32_e32 v68, v76, v68
	v_add_f32_e32 v136, v77, v68
	v_cvt_pk_bf16_f32 v68, v72, v73
	v_and_b32_e32 v150, v68, v196
	v_cvt_pk_bf16_f32 v68, v74, v75
	v_and_b32_e32 v151, v68, v196
	ds_read_b64_tr_b16 v[68:69], v197 offset:25600
	ds_read_b64_tr_b16 v[70:71], v197 offset:26112
	v_mfma_f32_32x32x16_bf16 v[100:115], v[172:175], v[120:123], v[100:115]
	v_add_f32_e32 v72, v78, v136
	v_add_f32_e32 v72, v79, v72
	v_add_f32_e32 v72, v80, v72
	v_add_f32_e32 v136, v81, v72
	v_cvt_pk_bf16_f32 v72, v76, v77
	v_and_b32_e32 v144, v72, v196
	v_cvt_pk_bf16_f32 v72, v78, v79
	v_and_b32_e32 v145, v72, v196
	ds_read_b64_tr_b16 v[72:73], v197 offset:29696
	ds_read_b64_tr_b16 v[74:75], v197 offset:30208
	v_mfma_f32_32x32x16_bf16 v[84:99], v[168:171], v[120:123], v[84:99]
	v_add_f32_e32 v76, v82, v136
	v_add_f32_e32 v76, v83, v76
	v_add_f32_e32 v76, v52, v76
	v_add_f32_e32 v136, v53, v76
	v_cvt_pk_bf16_f32 v76, v80, v81
	v_and_b32_e32 v146, v76, v196
	v_cvt_pk_bf16_f32 v76, v82, v83
	v_and_b32_e32 v147, v76, v196
	ds_read_b64_tr_b16 v[76:77], v197 offset:26624
	ds_read_b64_tr_b16 v[78:79], v197 offset:27136
	v_mfma_f32_32x32x16_bf16 v[100:115], v[164:167], v[124:127], v[100:115]
	v_add_f32_e32 v80, v54, v136
	v_add_f32_e32 v80, v55, v80
	v_cvt_pk_bf16_f32 v52, v52, v53
	v_add_f32_e32 v80, v56, v80
	v_and_b32_e32 v140, v52, v196
	v_cvt_pk_bf16_f32 v52, v54, v55
	v_add_f32_e32 v80, v57, v80
	v_and_b32_e32 v141, v52, v196
	ds_read_b64_tr_b16 v[52:53], v197 offset:30720
	ds_read_b64_tr_b16 v[54:55], v197 offset:31232
	v_mfma_f32_32x32x16_bf16 v[84:99], v[160:163], v[124:127], v[84:99]
	v_add_f32_e32 v80, v58, v80
	v_add_f32_e32 v80, v59, v80
	v_cvt_pk_bf16_f32 v56, v56, v57
	v_add_f32_e32 v80, v60, v80
	v_and_b32_e32 v142, v56, v196
	v_cvt_pk_bf16_f32 v56, v58, v59
	v_add_f32_e32 v80, v61, v80
	v_and_b32_e32 v143, v56, v196
	ds_read_b64_tr_b16 v[56:57], v197 offset:27648
	ds_read_b64_tr_b16 v[58:59], v197 offset:28160
	v_mfma_f32_32x32x16_bf16 v[100:115], v[156:159], v[128:131], v[100:115]
	v_add_f32_e32 v80, v62, v80
	v_add_f32_e32 v80, v63, v80
	v_cvt_pk_bf16_f32 v60, v60, v61
	v_add_f32_e32 v80, v64, v80
	v_and_b32_e32 v136, v60, v196
	v_cvt_pk_bf16_f32 v60, v62, v63
	v_add_f32_e32 v80, v65, v80
	v_and_b32_e32 v137, v60, v196
	ds_read_b64_tr_b16 v[60:61], v197 offset:31744
	ds_read_b64_tr_b16 v[62:63], v197 offset:32256
	v_mfma_f32_32x32x16_bf16 v[84:99], v[152:155], v[128:131], v[84:99]
	v_add_f32_e32 v80, v66, v80
	v_cvt_pk_bf16_f32 v64, v64, v65
	v_add_f32_e32 v80, v67, v80
	v_and_b32_e32 v138, v64, v196
	v_cvt_pk_bf16_f32 v64, v66, v67
	v_and_b32_e32 v139, v64, v196
	s_mov_b32 s22, 0xfffe0000
	s_mov_b32 s23, -1
	v_lshl_add_u64 v[64:65], v[194:195], 0, s[22:23]
	s_add_i32 s10, s25, s46
	s_mov_b32 m0, s10
	s_nop 0
	global_load_lds_dwordx4 v[64:65], off
	v_lshl_add_u64 v[64:65], v[192:193], 0, s[22:23]
	s_add_i32 s10, s24, s47
	s_mov_b32 m0, s10
	s_nop 0
	global_load_lds_dwordx4 v[64:65], off
	v_and_b32_e32 v66, v80, v196
	v_add_f32_e32 v204, v220, v66

.LBB0_801:
	v_mfma_f32_32x32x16_bf16 v[68:83], v[64:67], v[116:119], v[36:51]
	v_bfe_i32 v196, v132, s101, 1
	v_add_u32_e32 v197, s25, v219
	ds_read_b64_tr_b16 v[152:153], v197 offset:24576
	ds_read_b64_tr_b16 v[154:155], v197 offset:25088
	v_add_f32_e32 v52, v100, v101
	v_add_f32_e32 v52, v102, v52
	v_add_f32_e32 v52, v103, v52
	v_cvt_pk_bf16_f32 v53, v100, v101
	v_add_f32_e32 v52, v104, v52
	v_and_b32_e32 v148, v53, v196
	v_cvt_pk_bf16_f32 v53, v102, v103
	v_add_f32_e32 v52, v105, v52
	v_and_b32_e32 v149, v53, v196
	ds_read_b64_tr_b16 v[156:157], v197 offset:28672
	ds_read_b64_tr_b16 v[158:159], v197 offset:29184
	v_add_f32_e32 v52, v106, v52
	v_add_f32_e32 v52, v107, v52
	v_add_f32_e32 v52, v108, v52
	v_add_f32_e32 v136, v109, v52
	v_mfma_f32_32x32x16_bf16 v[52:67], v[180:183], v[116:119], v[36:51]
	v_cvt_pk_bf16_f32 v100, v104, v105
	v_and_b32_e32 v150, v100, v196
	v_cvt_pk_bf16_f32 v100, v106, v107
	v_and_b32_e32 v151, v100, v196
	ds_read_b64_tr_b16 v[100:101], v197 offset:25600
	ds_read_b64_tr_b16 v[102:103], v197 offset:26112
	v_mfma_f32_32x32x16_bf16 v[68:83], v[184:187], v[120:123], v[68:83]
	v_add_f32_e32 v104, v110, v136
	v_add_f32_e32 v104, v111, v104
	v_add_f32_e32 v104, v112, v104
	v_add_f32_e32 v136, v113, v104
	v_cvt_pk_bf16_f32 v104, v108, v109
	v_and_b32_e32 v144, v104, v196
	v_cvt_pk_bf16_f32 v104, v110, v111
	v_and_b32_e32 v145, v104, v196
	ds_read_b64_tr_b16 v[104:105], v197 offset:29696
	ds_read_b64_tr_b16 v[106:107], v197 offset:30208
	v_mfma_f32_32x32x16_bf16 v[52:67], v[176:179], v[120:123], v[52:67]
	v_add_f32_e32 v108, v114, v136
	v_add_f32_e32 v108, v115, v108
	v_add_f32_e32 v108, v84, v108
	v_add_f32_e32 v136, v85, v108
	v_cvt_pk_bf16_f32 v108, v112, v113
	v_and_b32_e32 v146, v108, v196
	v_cvt_pk_bf16_f32 v108, v114, v115
	v_and_b32_e32 v147, v108, v196
	ds_read_b64_tr_b16 v[108:109], v197 offset:26624
	ds_read_b64_tr_b16 v[110:111], v197 offset:27136
	v_mfma_f32_32x32x16_bf16 v[68:83], v[172:175], v[124:127], v[68:83]
	v_add_f32_e32 v112, v86, v136
	v_add_f32_e32 v112, v87, v112
	v_cvt_pk_bf16_f32 v84, v84, v85
	v_add_f32_e32 v112, v88, v112
	v_and_b32_e32 v140, v84, v196
	v_cvt_pk_bf16_f32 v84, v86, v87
	v_add_f32_e32 v112, v89, v112
	v_and_b32_e32 v141, v84, v196
	ds_read_b64_tr_b16 v[84:85], v197 offset:30720
	ds_read_b64_tr_b16 v[86:87], v197 offset:31232
	v_mfma_f32_32x32x16_bf16 v[52:67], v[168:171], v[124:127], v[52:67]
	v_add_f32_e32 v112, v90, v112
	v_add_f32_e32 v112, v91, v112
	v_cvt_pk_bf16_f32 v88, v88, v89
	v_add_f32_e32 v112, v92, v112
	v_and_b32_e32 v142, v88, v196
	v_cvt_pk_bf16_f32 v88, v90, v91
	v_add_f32_e32 v112, v93, v112
	v_and_b32_e32 v143, v88, v196
	ds_read_b64_tr_b16 v[88:89], v197 offset:27648
	ds_read_b64_tr_b16 v[90:91], v197 offset:28160
	v_mfma_f32_32x32x16_bf16 v[68:83], v[164:167], v[128:131], v[68:83]
	v_add_f32_e32 v112, v94, v112
	v_add_f32_e32 v112, v95, v112
	v_cvt_pk_bf16_f32 v92, v92, v93
	v_add_f32_e32 v112, v96, v112
	v_and_b32_e32 v136, v92, v196
	v_cvt_pk_bf16_f32 v92, v94, v95
	v_add_f32_e32 v112, v97, v112
	v_and_b32_e32 v137, v92, v196
	ds_read_b64_tr_b16 v[92:93], v197 offset:31744
	ds_read_b64_tr_b16 v[94:95], v197 offset:32256
	v_mfma_f32_32x32x16_bf16 v[52:67], v[160:163], v[128:131], v[52:67]
	v_add_f32_e32 v112, v98, v112
	v_cvt_pk_bf16_f32 v96, v96, v97
	v_add_f32_e32 v112, v99, v112
	v_and_b32_e32 v138, v96, v196
	v_cvt_pk_bf16_f32 v96, v98, v99
	v_and_b32_e32 v139, v96, v196
	v_and_b32_e32 v96, v112, v196
	v_add_f32_e32 v220, v204, v96
	s_add_i32 s10, s24, s46
	s_mov_b32 m0, s10
	s_nop 0
	global_load_lds_dwordx4 v[194:195], off
	s_add_i32 s10, s54, s47
	s_mov_b32 m0, s10
	s_nop 0
	global_load_lds_dwordx4 v[192:193], off
